# GEMM unit prologues: 128 accumulator VGPRs zeroed with 64 v_mov_b64 instead of 128 v_mov_b32
# baseline (speedup 1.0000x reference)
.LBB0_326:
	v_readlane_b32 s13, v230, 7
	s_add_u32 s28, s13, s16
	v_readlane_b32 s13, v230, 8
	s_addc_u32 s29, s13, s17
	s_and_b64 s[24:25], s[6:7], exec
	s_cselect_b32 s13, s29, s41
	s_cselect_b32 s15, s28, s40
	s_add_u32 s30, s26, s18
	s_addc_u32 s31, s27, s19
	s_and_b64 s[24:25], s[6:7], exec
	s_cselect_b32 s57, s31, s43
	s_cselect_b32 s58, s30, s42
	s_add_u32 s40, s40, 0x80080
	s_addc_u32 s41, s41, 0
	s_add_u32 s59, s42, 0x100
	v_mov_b64_e32 v[2:3], 0
	v_mov_b64_e32 v[4:5], 0
	v_mov_b64_e32 v[6:7], 0
	v_mov_b64_e32 v[8:9], 0
	v_mov_b64_e32 v[10:11], 0
	v_mov_b64_e32 v[12:13], 0
	v_mov_b64_e32 v[14:15], 0
	v_mov_b64_e32 v[16:17], 0
	v_mov_b64_e32 v[18:19], 0
	v_mov_b64_e32 v[20:21], 0
	v_mov_b64_e32 v[22:23], 0
	v_mov_b64_e32 v[24:25], 0
	v_mov_b64_e32 v[26:27], 0
	v_mov_b64_e32 v[28:29], 0
	v_mov_b64_e32 v[30:31], 0
	v_mov_b64_e32 v[32:33], 0
	v_mov_b64_e32 v[34:35], 0
	v_mov_b64_e32 v[36:37], 0
	v_mov_b64_e32 v[38:39], 0
	v_mov_b64_e32 v[40:41], 0
	v_mov_b64_e32 v[42:43], 0
	v_mov_b64_e32 v[44:45], 0
	v_mov_b64_e32 v[46:47], 0
	v_mov_b64_e32 v[48:49], 0
	v_mov_b64_e32 v[50:51], 0
	v_mov_b64_e32 v[52:53], 0
	v_mov_b64_e32 v[54:55], 0
	v_mov_b64_e32 v[56:57], 0
	v_mov_b64_e32 v[58:59], 0
	v_mov_b64_e32 v[60:61], 0
	v_mov_b64_e32 v[62:63], 0
	v_mov_b64_e32 v[64:65], 0
	v_mov_b64_e32 v[66:67], 0
	v_mov_b64_e32 v[68:69], 0
	v_mov_b64_e32 v[70:71], 0
	v_mov_b64_e32 v[72:73], 0
	v_mov_b64_e32 v[74:75], 0
	v_mov_b64_e32 v[76:77], 0
	v_mov_b64_e32 v[78:79], 0
	v_mov_b64_e32 v[80:81], 0
	v_mov_b64_e32 v[82:83], 0
	v_mov_b64_e32 v[84:85], 0
	v_mov_b64_e32 v[86:87], 0
	v_mov_b64_e32 v[88:89], 0
	v_mov_b64_e32 v[90:91], 0
	v_mov_b64_e32 v[92:93], 0
	v_mov_b64_e32 v[94:95], 0
	v_mov_b64_e32 v[96:97], 0
	v_mov_b64_e32 v[98:99], 0
	v_mov_b64_e32 v[100:101], 0
	v_mov_b64_e32 v[102:103], 0
	v_mov_b64_e32 v[104:105], 0
	v_mov_b64_e32 v[106:107], 0
	v_mov_b64_e32 v[108:109], 0
	v_mov_b64_e32 v[110:111], 0
	v_mov_b64_e32 v[112:113], 0
	v_mov_b64_e32 v[114:115], 0
	v_mov_b64_e32 v[116:117], 0
	v_mov_b64_e32 v[118:119], 0
	v_mov_b64_e32 v[120:121], 0
	v_mov_b64_e32 v[122:123], 0
	v_mov_b64_e32 v[124:125], 0
	v_mov_b64_e32 v[126:127], 0
	v_mov_b64_e32 v[128:129], 0
	s_addc_u32 s60, s43, 0
	s_mov_b32 s61, -2

.LBB0_423:
	s_add_u32 s44, s36, s28
	s_addc_u32 s45, s37, s29
	s_and_b64 s[24:25], s[42:43], exec
	s_cselect_b32 s74, s45, s7
	s_cselect_b32 s75, s44, s6
	s_add_u32 s46, s3, s30
	s_addc_u32 s47, s21, s31
	s_and_b64 s[24:25], s[42:43], exec
	s_cselect_b32 s76, s47, s49
	s_cselect_b32 s77, s46, s48
	s_add_i32 s78, s73, -2
	s_add_u32 s6, s6, 0x160080
	s_addc_u32 s7, s7, 0
	s_add_u32 s79, s48, 0x100
	v_mov_b64_e32 v[2:3], 0
	v_mov_b64_e32 v[4:5], 0
	v_mov_b64_e32 v[6:7], 0
	v_mov_b64_e32 v[8:9], 0
	v_mov_b64_e32 v[10:11], 0
	v_mov_b64_e32 v[12:13], 0
	v_mov_b64_e32 v[14:15], 0
	v_mov_b64_e32 v[16:17], 0
	v_mov_b64_e32 v[18:19], 0
	v_mov_b64_e32 v[20:21], 0
	v_mov_b64_e32 v[22:23], 0
	v_mov_b64_e32 v[24:25], 0
	v_mov_b64_e32 v[26:27], 0
	v_mov_b64_e32 v[28:29], 0
	v_mov_b64_e32 v[30:31], 0
	v_mov_b64_e32 v[32:33], 0
	v_mov_b64_e32 v[34:35], 0
	v_mov_b64_e32 v[36:37], 0
	v_mov_b64_e32 v[38:39], 0
	v_mov_b64_e32 v[40:41], 0
	v_mov_b64_e32 v[42:43], 0
	v_mov_b64_e32 v[44:45], 0
	v_mov_b64_e32 v[46:47], 0
	v_mov_b64_e32 v[48:49], 0
	v_mov_b64_e32 v[50:51], 0
	v_mov_b64_e32 v[52:53], 0
	v_mov_b64_e32 v[54:55], 0
	v_mov_b64_e32 v[56:57], 0
	v_mov_b64_e32 v[58:59], 0
	v_mov_b64_e32 v[60:61], 0
	v_mov_b64_e32 v[62:63], 0
	v_mov_b64_e32 v[64:65], 0
	v_mov_b64_e32 v[66:67], 0
	v_mov_b64_e32 v[68:69], 0
	v_mov_b64_e32 v[70:71], 0
	v_mov_b64_e32 v[72:73], 0
	v_mov_b64_e32 v[74:75], 0
	v_mov_b64_e32 v[76:77], 0
	v_mov_b64_e32 v[78:79], 0
	v_mov_b64_e32 v[80:81], 0
	v_mov_b64_e32 v[82:83], 0
	v_mov_b64_e32 v[84:85], 0
	v_mov_b64_e32 v[86:87], 0
	v_mov_b64_e32 v[88:89], 0
	v_mov_b64_e32 v[90:91], 0
	v_mov_b64_e32 v[92:93], 0
	v_mov_b64_e32 v[94:95], 0
	v_mov_b64_e32 v[96:97], 0
	v_mov_b64_e32 v[98:99], 0
	v_mov_b64_e32 v[100:101], 0
	v_mov_b64_e32 v[102:103], 0
	v_mov_b64_e32 v[104:105], 0
	v_mov_b64_e32 v[106:107], 0
	v_mov_b64_e32 v[108:109], 0
	v_mov_b64_e32 v[110:111], 0
	v_mov_b64_e32 v[112:113], 0
	v_mov_b64_e32 v[114:115], 0
	v_mov_b64_e32 v[116:117], 0
	v_mov_b64_e32 v[118:119], 0
	v_mov_b64_e32 v[120:121], 0
	v_mov_b64_e32 v[122:123], 0
	v_mov_b64_e32 v[124:125], 0
	v_mov_b64_e32 v[126:127], 0
	v_mov_b64_e32 v[128:129], 0
	s_addc_u32 s80, s49, 0
	s_mov_b32 s24, 0

.LBB0_586:
	v_readlane_b32 s23, v230, 7
	s_add_u32 s52, s23, s42
	v_readlane_b32 s23, v230, 8
	s_addc_u32 s53, s23, s43
	s_and_b64 s[24:25], s[50:51], exec
	s_cselect_b32 s39, s53, s57
	s_cselect_b32 s49, s52, s56
	s_add_u32 s54, s3, s44
	s_addc_u32 s55, s21, s45
	s_and_b64 s[24:25], s[50:51], exec
	s_cselect_b32 s80, s55, s59
	s_cselect_b32 s81, s54, s58
	s_add_i32 s82, s78, -2
	s_add_u32 s56, s56, 0x80080
	s_addc_u32 s57, s57, 0
	s_add_u32 s83, s58, 0x100
	v_mov_b64_e32 v[2:3], 0
	v_mov_b64_e32 v[4:5], 0
	v_mov_b64_e32 v[6:7], 0
	v_mov_b64_e32 v[8:9], 0
	v_mov_b64_e32 v[10:11], 0
	v_mov_b64_e32 v[12:13], 0
	v_mov_b64_e32 v[14:15], 0
	v_mov_b64_e32 v[16:17], 0
	v_mov_b64_e32 v[18:19], 0
	v_mov_b64_e32 v[20:21], 0
	v_mov_b64_e32 v[22:23], 0
	v_mov_b64_e32 v[24:25], 0
	v_mov_b64_e32 v[26:27], 0
	v_mov_b64_e32 v[28:29], 0
	v_mov_b64_e32 v[30:31], 0
	v_mov_b64_e32 v[32:33], 0
	v_mov_b64_e32 v[34:35], 0
	v_mov_b64_e32 v[36:37], 0
	v_mov_b64_e32 v[38:39], 0
	v_mov_b64_e32 v[40:41], 0
	v_mov_b64_e32 v[42:43], 0
	v_mov_b64_e32 v[44:45], 0
	v_mov_b64_e32 v[46:47], 0
	v_mov_b64_e32 v[48:49], 0
	v_mov_b64_e32 v[50:51], 0
	v_mov_b64_e32 v[52:53], 0
	v_mov_b64_e32 v[54:55], 0
	v_mov_b64_e32 v[56:57], 0
	v_mov_b64_e32 v[58:59], 0
	v_mov_b64_e32 v[60:61], 0
	v_mov_b64_e32 v[62:63], 0
	v_mov_b64_e32 v[64:65], 0
	v_mov_b64_e32 v[66:67], 0
	v_mov_b64_e32 v[68:69], 0
	v_mov_b64_e32 v[70:71], 0
	v_mov_b64_e32 v[72:73], 0
	v_mov_b64_e32 v[74:75], 0
	v_mov_b64_e32 v[76:77], 0
	v_mov_b64_e32 v[78:79], 0
	v_mov_b64_e32 v[80:81], 0
	v_mov_b64_e32 v[82:83], 0
	v_mov_b64_e32 v[84:85], 0
	v_mov_b64_e32 v[86:87], 0
	v_mov_b64_e32 v[88:89], 0
	v_mov_b64_e32 v[90:91], 0
	v_mov_b64_e32 v[92:93], 0
	v_mov_b64_e32 v[94:95], 0
	v_mov_b64_e32 v[96:97], 0
	v_mov_b64_e32 v[98:99], 0
	v_mov_b64_e32 v[100:101], 0
	v_mov_b64_e32 v[102:103], 0
	v_mov_b64_e32 v[104:105], 0
	v_mov_b64_e32 v[106:107], 0
	v_mov_b64_e32 v[108:109], 0
	v_mov_b64_e32 v[110:111], 0
	v_mov_b64_e32 v[112:113], 0
	v_mov_b64_e32 v[114:115], 0
	v_mov_b64_e32 v[116:117], 0
	v_mov_b64_e32 v[118:119], 0
	v_mov_b64_e32 v[120:121], 0
	v_mov_b64_e32 v[122:123], 0
	v_mov_b64_e32 v[124:125], 0
	v_mov_b64_e32 v[126:127], 0
	v_mov_b64_e32 v[128:129], 0
	s_addc_u32 s84, s59, 0
	s_mov_b32 s24, 0

.LBB0_994:
	s_add_u32 s42, s3, s16
	s_addc_u32 s43, s21, s17
	s_and_b64 s[24:25], s[38:39], exec
	s_cselect_b32 s15, s43, s49
	s_cselect_b32 s31, s42, s48
	s_add_u32 s44, s33, s18
	s_addc_u32 s45, s47, s19
	s_and_b64 s[24:25], s[38:39], exec
	s_cselect_b32 s73, s45, s51
	s_cselect_b32 s74, s44, s50
	s_add_i32 s75, s72, -2
	s_add_u32 s48, s48, 0x80080
	s_addc_u32 s49, s49, 0
	s_add_u32 s76, s50, 0x100
	v_mov_b64_e32 v[2:3], 0
	v_mov_b64_e32 v[4:5], 0
	v_mov_b64_e32 v[6:7], 0
	v_mov_b64_e32 v[8:9], 0
	v_mov_b64_e32 v[10:11], 0
	v_mov_b64_e32 v[12:13], 0
	v_mov_b64_e32 v[14:15], 0
	v_mov_b64_e32 v[16:17], 0
	v_mov_b64_e32 v[18:19], 0
	v_mov_b64_e32 v[20:21], 0
	v_mov_b64_e32 v[22:23], 0
	v_mov_b64_e32 v[24:25], 0
	v_mov_b64_e32 v[26:27], 0
	v_mov_b64_e32 v[28:29], 0
	v_mov_b64_e32 v[30:31], 0
	v_mov_b64_e32 v[32:33], 0
	v_mov_b64_e32 v[34:35], 0
	v_mov_b64_e32 v[36:37], 0
	v_mov_b64_e32 v[38:39], 0
	v_mov_b64_e32 v[40:41], 0
	v_mov_b64_e32 v[42:43], 0
	v_mov_b64_e32 v[44:45], 0
	v_mov_b64_e32 v[46:47], 0
	v_mov_b64_e32 v[48:49], 0
	v_mov_b64_e32 v[50:51], 0
	v_mov_b64_e32 v[52:53], 0
	v_mov_b64_e32 v[54:55], 0
	v_mov_b64_e32 v[56:57], 0
	v_mov_b64_e32 v[58:59], 0
	v_mov_b64_e32 v[60:61], 0
	v_mov_b64_e32 v[62:63], 0
	v_mov_b64_e32 v[64:65], 0
	v_mov_b64_e32 v[66:67], 0
	v_mov_b64_e32 v[68:69], 0
	v_mov_b64_e32 v[70:71], 0
	v_mov_b64_e32 v[72:73], 0
	v_mov_b64_e32 v[74:75], 0
	v_mov_b64_e32 v[76:77], 0
	v_mov_b64_e32 v[78:79], 0
	v_mov_b64_e32 v[80:81], 0
	v_mov_b64_e32 v[82:83], 0
	v_mov_b64_e32 v[84:85], 0
	v_mov_b64_e32 v[86:87], 0
	v_mov_b64_e32 v[88:89], 0
	v_mov_b64_e32 v[90:91], 0
	v_mov_b64_e32 v[92:93], 0
	v_mov_b64_e32 v[94:95], 0
	v_mov_b64_e32 v[96:97], 0
	v_mov_b64_e32 v[98:99], 0
	v_mov_b64_e32 v[100:101], 0
	v_mov_b64_e32 v[102:103], 0
	v_mov_b64_e32 v[104:105], 0
	v_mov_b64_e32 v[106:107], 0
	v_mov_b64_e32 v[108:109], 0
	v_mov_b64_e32 v[110:111], 0
	v_mov_b64_e32 v[112:113], 0
	v_mov_b64_e32 v[114:115], 0
	v_mov_b64_e32 v[116:117], 0
	v_mov_b64_e32 v[118:119], 0
	v_mov_b64_e32 v[120:121], 0
	v_mov_b64_e32 v[122:123], 0
	v_mov_b64_e32 v[124:125], 0
	v_mov_b64_e32 v[126:127], 0
	v_mov_b64_e32 v[128:129], 0
	s_addc_u32 s77, s51, 0
	s_mov_b32 s24, 0
	s_waitcnt vmcnt(0)

.LBB0_1148:
	v_readlane_b32 s13, v230, 7
	s_add_u32 s28, s13, s16
	v_readlane_b32 s13, v230, 8
	s_addc_u32 s29, s13, s17
	s_and_b64 s[24:25], s[6:7], exec
	s_cselect_b32 s13, s29, s43
	s_cselect_b32 s15, s28, s42
	s_add_u32 s30, s21, s18
	s_addc_u32 s31, s33, s19
	s_and_b64 s[24:25], s[6:7], exec
	s_cselect_b32 s60, s31, s45
	s_cselect_b32 s61, s30, s44
	s_add_u32 s42, s42, 0x80080
	s_addc_u32 s43, s43, 0
	s_add_u32 s62, s44, 0x100
	v_mov_b64_e32 v[2:3], 0
	v_mov_b64_e32 v[4:5], 0
	v_mov_b64_e32 v[6:7], 0
	v_mov_b64_e32 v[8:9], 0
	v_mov_b64_e32 v[10:11], 0
	v_mov_b64_e32 v[12:13], 0
	v_mov_b64_e32 v[14:15], 0
	v_mov_b64_e32 v[16:17], 0
	v_mov_b64_e32 v[18:19], 0
	v_mov_b64_e32 v[20:21], 0
	v_mov_b64_e32 v[22:23], 0
	v_mov_b64_e32 v[24:25], 0
	v_mov_b64_e32 v[26:27], 0
	v_mov_b64_e32 v[28:29], 0
	v_mov_b64_e32 v[30:31], 0
	v_mov_b64_e32 v[32:33], 0
	v_mov_b64_e32 v[34:35], 0
	v_mov_b64_e32 v[36:37], 0
	v_mov_b64_e32 v[38:39], 0
	v_mov_b64_e32 v[40:41], 0
	v_mov_b64_e32 v[42:43], 0
	v_mov_b64_e32 v[44:45], 0
	v_mov_b64_e32 v[46:47], 0
	v_mov_b64_e32 v[48:49], 0
	v_mov_b64_e32 v[50:51], 0
	v_mov_b64_e32 v[52:53], 0
	v_mov_b64_e32 v[54:55], 0
	v_mov_b64_e32 v[56:57], 0
	v_mov_b64_e32 v[58:59], 0
	v_mov_b64_e32 v[60:61], 0
	v_mov_b64_e32 v[62:63], 0
	v_mov_b64_e32 v[64:65], 0
	v_mov_b64_e32 v[66:67], 0
	v_mov_b64_e32 v[68:69], 0
	v_mov_b64_e32 v[70:71], 0
	v_mov_b64_e32 v[72:73], 0
	v_mov_b64_e32 v[74:75], 0
	v_mov_b64_e32 v[76:77], 0
	v_mov_b64_e32 v[78:79], 0
	v_mov_b64_e32 v[80:81], 0
	v_mov_b64_e32 v[82:83], 0
	v_mov_b64_e32 v[84:85], 0
	v_mov_b64_e32 v[86:87], 0
	v_mov_b64_e32 v[88:89], 0
	v_mov_b64_e32 v[90:91], 0
	v_mov_b64_e32 v[92:93], 0
	v_mov_b64_e32 v[94:95], 0
	v_mov_b64_e32 v[96:97], 0
	v_mov_b64_e32 v[98:99], 0
	v_mov_b64_e32 v[100:101], 0
	v_mov_b64_e32 v[102:103], 0
	v_mov_b64_e32 v[104:105], 0
	v_mov_b64_e32 v[106:107], 0
	v_mov_b64_e32 v[108:109], 0
	v_mov_b64_e32 v[110:111], 0
	v_mov_b64_e32 v[112:113], 0
	v_mov_b64_e32 v[114:115], 0
	v_mov_b64_e32 v[116:117], 0
	v_mov_b64_e32 v[118:119], 0
	v_mov_b64_e32 v[120:121], 0
	v_mov_b64_e32 v[122:123], 0
	v_mov_b64_e32 v[124:125], 0
	v_mov_b64_e32 v[126:127], 0
	v_mov_b64_e32 v[128:129], 0
	s_addc_u32 s63, s45, 0
	s_mov_b32 s64, -2

.LBB0_1247:
	s_add_u32 s30, s36, s14
	s_addc_u32 s31, s37, s15
	s_and_b64 s[24:25], s[28:29], exec
	s_cselect_b32 s66, s31, s39
	s_cselect_b32 s67, s30, s38
	s_add_u32 s34, s3, s16
	s_addc_u32 s35, s21, s17
	s_and_b64 s[24:25], s[28:29], exec
	s_cselect_b32 s68, s35, s43
	s_cselect_b32 s69, s34, s42
	s_add_i32 s70, s65, -2
	s_add_u32 s38, s38, 0x160080
	s_addc_u32 s39, s39, 0
	s_add_u32 s71, s42, 0x100
	v_mov_b64_e32 v[0:1], 0
	v_mov_b64_e32 v[2:3], 0
	v_mov_b64_e32 v[4:5], 0
	v_mov_b64_e32 v[6:7], 0
	v_mov_b64_e32 v[8:9], 0
	v_mov_b64_e32 v[10:11], 0
	v_mov_b64_e32 v[12:13], 0
	v_mov_b64_e32 v[14:15], 0
	v_mov_b64_e32 v[16:17], 0
	v_mov_b64_e32 v[18:19], 0
	v_mov_b64_e32 v[20:21], 0
	v_mov_b64_e32 v[22:23], 0
	v_mov_b64_e32 v[24:25], 0
	v_mov_b64_e32 v[26:27], 0
	v_mov_b64_e32 v[28:29], 0
	v_mov_b64_e32 v[30:31], 0
	v_mov_b64_e32 v[32:33], 0
	v_mov_b64_e32 v[34:35], 0
	v_mov_b64_e32 v[36:37], 0
	v_mov_b64_e32 v[38:39], 0
	v_mov_b64_e32 v[40:41], 0
	v_mov_b64_e32 v[42:43], 0
	v_mov_b64_e32 v[44:45], 0
	v_mov_b64_e32 v[46:47], 0
	v_mov_b64_e32 v[48:49], 0
	v_mov_b64_e32 v[50:51], 0
	v_mov_b64_e32 v[52:53], 0
	v_mov_b64_e32 v[54:55], 0
	v_mov_b64_e32 v[56:57], 0
	v_mov_b64_e32 v[58:59], 0
	v_mov_b64_e32 v[60:61], 0
	v_mov_b64_e32 v[62:63], 0
	v_mov_b64_e32 v[64:65], 0
	v_mov_b64_e32 v[66:67], 0
	v_mov_b64_e32 v[68:69], 0
	v_mov_b64_e32 v[70:71], 0
	v_mov_b64_e32 v[72:73], 0
	v_mov_b64_e32 v[74:75], 0
	v_mov_b64_e32 v[76:77], 0
	v_mov_b64_e32 v[78:79], 0
	v_mov_b64_e32 v[80:81], 0
	v_mov_b64_e32 v[82:83], 0
	v_mov_b64_e32 v[84:85], 0
	v_mov_b64_e32 v[86:87], 0
	v_mov_b64_e32 v[88:89], 0
	v_mov_b64_e32 v[90:91], 0
	v_mov_b64_e32 v[92:93], 0
	v_mov_b64_e32 v[94:95], 0
	v_mov_b64_e32 v[96:97], 0
	v_mov_b64_e32 v[98:99], 0
	v_mov_b64_e32 v[100:101], 0
	v_mov_b64_e32 v[102:103], 0
	v_mov_b64_e32 v[104:105], 0
	v_mov_b64_e32 v[106:107], 0
	v_mov_b64_e32 v[108:109], 0
	v_mov_b64_e32 v[110:111], 0
	v_mov_b64_e32 v[112:113], 0
	v_mov_b64_e32 v[114:115], 0
	v_mov_b64_e32 v[116:117], 0
	v_mov_b64_e32 v[118:119], 0
	v_mov_b64_e32 v[120:121], 0
	v_mov_b64_e32 v[122:123], 0
	v_mov_b64_e32 v[124:125], 0
	v_mov_b64_e32 v[126:127], 0
	s_addc_u32 s72, s43, 0
	s_mov_b32 s24, 0
	s_waitcnt vmcnt(0)
